# attention ring DMA: scalar-formed source addresses (saddr form, base in s[100:101]) replacing two v_mad_i64_i32; dead M0 save/restore removed; stacked
# speedup vs baseline: 1.0089x; 1.0001x over previous
; #define ATT_DMA(i, slot) do { if (ABL & 1) break; const long off_ = (long)ATT_TAU(i) * KVBLK * INW; \
;         glds16(ksrc + off_, (unsigned)__builtin_amdgcn_readfirstlane(kdst + (slot) * SLOTB)); glds16(vsrc + off_, (unsigned)__builtin_amdgcn_readfirstlane(vdst + (slot) * SLOTB)); } while (0)
;     ...
;     for (int i = 1; i < NTe; ++i) {
;         const int tau = ATT_TAU(i), slot = i & 3;
;         { const int id_ = i + 2 < NTe ? i + 2 : NTe - 1; ATT_DMA(id_, (i + 2) & 3); }
;         { const lds_cptr vp = vp0 + ((i - 1) & 3) * SLOTB, kp = kp0 + slot * SLOTB;
.LBB0_334:
	v_lshlrev_b32_e32 v0, 5, v93
	v_and_b32_e32 v0, 32, v0
	v_or_b32_e32 v1, v172, v97
	v_add_u32_e32 v0, 0, v0
	v_lshlrev_b32_e32 v1, 6, v1
	v_mov_b32_e32 v15, 0
	v_add3_u32 v191, v0, v104, v1
	s_andn2_b64 vcc, exec, s[36:37]
	v_lshl_add_u32 v190, v170, 2, s20
	v_lshl_add_u32 v185, v172, 2, s20
	v_mov_b32_e32 v14, v15
	v_mov_b32_e32 v13, v15
	v_mov_b32_e32 v12, v15
	v_mov_b32_e32 v11, v15
	v_mov_b32_e32 v10, v15
	v_mov_b32_e32 v9, v15
	v_mov_b32_e32 v8, v15
	v_mov_b32_e32 v7, v15
	v_mov_b32_e32 v6, v15
	v_mov_b32_e32 v5, v15
	v_mov_b32_e32 v4, v15
	v_mov_b32_e32 v3, v15
	v_mov_b32_e32 v2, v15
	v_mov_b32_e32 v1, v15
	v_mov_b32_e32 v0, v15
	v_mov_b32_e32 v31, v15
	v_mov_b32_e32 v30, v15
	v_mov_b32_e32 v29, v15
	v_mov_b32_e32 v28, v15
	v_mov_b32_e32 v27, v15
	v_mov_b32_e32 v26, v15
	v_mov_b32_e32 v25, v15
	v_mov_b32_e32 v24, v15
	v_mov_b32_e32 v23, v15
	v_mov_b32_e32 v22, v15
	v_mov_b32_e32 v21, v15
	v_mov_b32_e32 v20, v15
	v_mov_b32_e32 v19, v15
	v_mov_b32_e32 v18, v15
	v_mov_b32_e32 v17, v15
	v_mov_b32_e32 v16, v15
	v_mov_b32_e32 v47, v15
	v_mov_b32_e32 v46, v15
	v_mov_b32_e32 v45, v15
	v_mov_b32_e32 v44, v15
	v_mov_b32_e32 v43, v15
	v_mov_b32_e32 v42, v15
	v_mov_b32_e32 v41, v15
	v_mov_b32_e32 v40, v15
	v_mov_b32_e32 v39, v15
	v_mov_b32_e32 v38, v15
	v_mov_b32_e32 v37, v15
	v_mov_b32_e32 v36, v15
	v_mov_b32_e32 v35, v15
	v_mov_b32_e32 v34, v15
	v_mov_b32_e32 v33, v15
	v_mov_b32_e32 v32, v15
	v_mov_b32_e32 v63, v15
	v_mov_b32_e32 v62, v15
	v_mov_b32_e32 v61, v15
	v_mov_b32_e32 v60, v15
	v_mov_b32_e32 v59, v15
	v_mov_b32_e32 v58, v15
	v_mov_b32_e32 v57, v15
	v_mov_b32_e32 v56, v15
	v_mov_b32_e32 v55, v15
	v_mov_b32_e32 v54, v15
	v_mov_b32_e32 v53, v15
	v_mov_b32_e32 v52, v15
	v_mov_b32_e32 v51, v15
	v_mov_b32_e32 v50, v15
	v_mov_b32_e32 v49, v15
	v_mov_b32_e32 v48, v15
	s_cbranch_vccnz .LBB0_368
	v_cvt_pk_bf16_f32 v4, v98, 0
	v_cndmask_b32_e64 v1, v175, v176, s[40:41]
	v_lshlrev_b32_e32 v4, 16, v4
	v_cndmask_b32_e64 v1, v1, 0, s[62:63]
	v_sub_f32_e32 v4, v98, v4
	v_cvt_pk_bf16_f32 v5, v4, 0
	v_cndmask_b32_e64 v128, 0, v1, s[38:39]
	v_cvt_pk_bf16_f32 v1, v99, 0
	v_cndmask_b32_e64 v2, v177, v178, s[40:41]
	v_lshlrev_b32_e32 v5, 16, v5
	v_lshlrev_b32_e32 v1, 16, v1
	v_cndmask_b32_e64 v2, v2, 0, s[62:63]
	v_sub_f32_e32 v5, v4, v5
	v_cvt_pk_bf16_f32 v4, v98, v4
	v_sub_f32_e32 v1, v99, v1
	v_cndmask_b32_e64 v126, v2, v4, s[38:39]
	v_cvt_pk_bf16_f32 v4, v1, 0
	v_cndmask_b32_e64 v0, v173, -v173, s[40:41]
	v_lshlrev_b32_e32 v4, 16, v4
	v_cndmask_b32_e64 v0, v0, 0, s[62:63]
	v_cndmask_b32_e64 v3, v179, v180, s[40:41]
	v_sub_f32_e32 v4, v1, v4
	v_cndmask_b32_e64 v3, v3, 0, s[62:63]
	v_cvt_pk_bf16_f32 v5, v5, v0
	v_cvt_pk_bf16_f32 v0, v4, v0
	s_or_b32 s21, s21, 64
	v_cndmask_b32_e64 v139, v3, v0, s[38:39]
	v_cvt_f32_u32_e32 v0, s21
	v_cvt_pk_bf16_f32 v1, v99, v1
	v_cndmask_b32_e64 v138, v2, v1, s[38:39]
	s_sub_i32 s20, 64, s14
	v_lshrrev_b32_e32 v1, 16, v0
	v_and_b32_e32 v0, 0x7fff0000, v0
	v_or_b32_e32 v0, v1, v0
	v_cndmask_b32_e64 v127, v3, v5, s[38:39]
	v_cndmask_b32_e64 v130, v0, v96, s[38:39]
	s_sub_i32 s27, s15, s23
	v_xor_b32_e32 v154, 0x80000000, v92
	v_mov_b32_e32 v0, 0
	v_mov_b64_e32 v[144:145], v[128:129]
	s_sub_i32 s19, 64, s23
	v_mov_b32_e32 v140, v128
	v_mov_b32_e32 v141, v129
	v_cndmask_b32_e64 v131, v1, v95, s[38:39]
	v_mov_b32_e32 v133, v129
	v_cndmask_b32_e64 v135, v1, v94, s[38:39]
	v_mov_b32_e32 v134, v130
	v_mov_b32_e32 v137, v129
	s_add_i32 s21, s22, s15
	s_add_i32 s22, s27, 63
	s_sub_i32 s23, 63, s14
	s_max_i32 s26, s20, 2
	v_mov_b32_e32 v156, v154
	v_mov_b32_e32 v157, v154
	s_add_i32 s27, s27, 62
	s_mov_b32 s28, 1
	s_mov_b32 s29, 0x8000
	v_mov_b64_e32 v[142:143], v[126:127]
	v_mov_b32_e32 v1, v0
	v_mov_b32_e32 v2, v0
	v_mov_b32_e32 v3, v0
	v_mov_b32_e32 v4, v0
	v_mov_b32_e32 v5, v0
	v_mov_b32_e32 v6, v0
	v_mov_b32_e32 v7, v0
	v_mov_b32_e32 v8, v0
	v_mov_b32_e32 v9, v0
	v_mov_b32_e32 v10, v0
	v_mov_b32_e32 v11, v0
	v_mov_b32_e32 v12, v0
	v_mov_b32_e32 v13, v0
	v_mov_b32_e32 v14, v0
	v_mov_b32_e32 v15, v0
	v_mov_b32_e32 v16, v0
	v_mov_b32_e32 v17, v0
	v_mov_b32_e32 v18, v0
	v_mov_b32_e32 v19, v0
	v_mov_b32_e32 v20, v0
	v_mov_b32_e32 v21, v0
	v_mov_b32_e32 v22, v0
	v_mov_b32_e32 v23, v0
	v_mov_b32_e32 v24, v0
	v_mov_b32_e32 v25, v0
	v_mov_b32_e32 v26, v0
	v_mov_b32_e32 v27, v0
	v_mov_b32_e32 v28, v0
	v_mov_b32_e32 v29, v0
	v_mov_b32_e32 v30, v0
	v_mov_b32_e32 v31, v0
	v_mov_b32_e32 v32, v0
	v_mov_b32_e32 v33, v0
	v_mov_b32_e32 v34, v0
	v_mov_b32_e32 v35, v0
	v_mov_b32_e32 v36, v0
	v_mov_b32_e32 v37, v0
	v_mov_b32_e32 v38, v0
	v_mov_b32_e32 v39, v0
	v_mov_b32_e32 v40, v0
	v_mov_b32_e32 v41, v0
	v_mov_b32_e32 v42, v0
	v_mov_b32_e32 v43, v0
	v_mov_b32_e32 v44, v0
	v_mov_b32_e32 v45, v0
	v_mov_b32_e32 v46, v0
	v_mov_b32_e32 v47, v0
	v_mov_b32_e32 v48, v0
	v_mov_b32_e32 v49, v0
	v_mov_b32_e32 v50, v0
	v_mov_b32_e32 v51, v0
	v_mov_b32_e32 v52, v0
	v_mov_b32_e32 v53, v0
	v_mov_b32_e32 v54, v0
	v_mov_b32_e32 v55, v0
	v_mov_b32_e32 v56, v0
	v_mov_b32_e32 v57, v0
	v_mov_b32_e32 v58, v0
	v_mov_b32_e32 v59, v0
	v_mov_b32_e32 v60, v0
	v_mov_b32_e32 v61, v0
	v_mov_b32_e32 v62, v0
	v_mov_b32_e32 v63, v0
	v_readfirstlane_b32 s100, v148
	v_readfirstlane_b32 s101, v149
	s_nop 1
	v_subrev_u32_e32 v146, s100, v146
	v_subrev_u32_e32 v148, s100, v148
	s_branch .LBB0_339

; #define ATT_DMA(i, slot) do { if (ABL & 1) break; const long off_ = (long)ATT_TAU(i) * KVBLK * INW; \
;         glds16(ksrc + off_, (unsigned)__builtin_amdgcn_readfirstlane(kdst + (slot) * SLOTB)); glds16(vsrc + off_, (unsigned)__builtin_amdgcn_readfirstlane(vdst + (slot) * SLOTB)); } while (0)
; #define ATT_BARV(N) do { if (ABL & 16) asm volatile("s_waitcnt vmcnt(" #N ") lgkmcnt(0)\n\ts_nop 11" ::: "memory"); else asm volatile("s_waitcnt vmcnt(" #N ") lgkmcnt(0)\n\ts_barrier\n\ts_nop 11" ::: "memory"); } while (0)
; #define ATT_SB() __builtin_amdgcn_sched_barrier(0)
; #define ATT_LDQ() const bf16x8 qf0 = *(const __attribute__((address_space(3))) bf16x8*)(qp), qf1 = *(const __attribute__((address_space(3))) bf16x8*)(qp + 1024), qf2 = *(const __attribute__((address_space(3))) bf16x8*)(qp + 2048), qf3 = *(const __attribute__((address_space(3))) bf16x8*)(qp + 3072)
; #define ATT_KA(off) (*(const __attribute__((address_space(3))) bf16x8*)(kp + (off)))
; #define ATT_KB(off) (*(const __attribute__((address_space(3))) bf16x8*)(kp + koB + (off)))
; #define ATT_VFR(n, ks) const s16x4 l0##n = vtr(vp + (ks) * 1024), h0##n = vtr(vp + (ks) * 1024 + 512), l1##n = vtr(vp + 4096 + (ks) * 1024), h1##n = vtr(vp + 4096 + (ks) * 1024 + 512)
;     ...
;     for (int i = 1; i < NTe; ++i) {
;         const int tau = ATT_TAU(i), slot = i & 3;
;         { const int id_ = i + 2 < NTe ? i + 2 : NTe - 1; ATT_DMA(id_, (i + 2) & 3); }
;         { const lds_cptr vp = vp0 + ((i - 1) & 3) * SLOTB, kp = kp0 + slot * SLOTB;
;           ATT_VFR(a, 0); ATT_VFR(b, 1);
;           const bf16x8 ka0 = ATT_KA(0), ka1 = ATT_KA(2048), ka2 = ATT_KB(0), ka3 = ATT_KB(2048);
;           ATT_SB();
;           ATT_PVK(a, pa0, pb0); ATT_SB();
;           ATT_VFR(c, 2); ATT_SB();
;           ATT_PVK(b, pa1, pb1); ATT_SB();
;           ATT_VFR(d, 3);
;           const bf16x8 kb0 = ATT_KA(4096), kb1 = ATT_KA(6144), kb2 = ATT_KB(4096), kb3 = ATT_KB(6144);
;           ATT_LDQ();
;           ATT_SB();
;           ATT_PVK(c, pa2, pb2); ATT_SB();
;           ATT_PVK(d, pa3, pb3); ATT_SB();
;           ATT_QKA(); ATT_QKB(); }
;         ATT_SB();
;         ATT_BARV(2);
;         __builtin_amdgcn_s_setprio(1);
;         ATT_SB();
.LBB0_339:
	s_add_i32 s30, s15, s28
	s_cmp_lt_i32 s28, s19
	s_cselect_b32 s30, s30, s27
	s_add_i32 s31, s28, 2
	s_cmp_lt_i32 s31, s20
	s_cselect_b32 s34, s31, s23
	s_add_i32 s35, s34, s15
	s_sub_i32 s36, s22, s34
	s_cmp_lt_i32 s34, s19
	s_cselect_b32 s36, s35, s36
	s_add_i32 s34, s29, 0xffffa000
	s_and_b32 s35, s29, 0x6000
	v_add_u32_e32 v112, s35, v191
	s_and_b32 s34, s34, 0x6000
	v_add_u32_e32 v197, s34, v181
	ds_read_b64_tr_b16 v[92:93], v112 offset:32768
	ds_read_b64_tr_b16 v[94:95], v112 offset:33280
	ds_read_b64_tr_b16 v[96:97], v112 offset:33792
	ds_read_b64_tr_b16 v[98:99], v112 offset:34304
	ds_read_b64_tr_b16 v[104:105], v112 offset:36864
	ds_read_b64_tr_b16 v[106:107], v112 offset:37376
	ds_read_b64_tr_b16 v[108:109], v112 offset:37888
	ds_read_b64_tr_b16 v[110:111], v112 offset:38400
	ds_read_b128 v[158:161], v197
	ds_read_b128 v[192:195], v197 offset:2048
	v_add_u32_e32 v196, v197, v183
	ds_read_b128 v[198:201], v196
	ds_read_b128 v[202:205], v196 offset:2048
	s_waitcnt lgkmcnt(10)
	v_mfma_f32_32x32x16_bf16 v[48:63], v[88:91], v[92:95], v[48:63]
	s_waitcnt lgkmcnt(6)
	v_mfma_f32_32x32x16_bf16 v[32:47], v[88:91], v[104:107], v[32:47]
	v_mfma_f32_32x32x16_bf16 v[16:31], v[100:103], v[92:95], v[16:31]
	v_mfma_f32_32x32x16_bf16 v[0:15], v[100:103], v[104:107], v[0:15]
	s_mul_i32 s34, s36, 0x50000
	s_add_u32 s34, s100, s34
	s_addc_u32 s35, s101, 0
	s_add_i32 s37, s29, 0xffffe000
	s_and_b32 s37, s37, 0x6000
	s_add_i32 m0, s37, s45
	s_nop 0
	global_load_lds_dwordx4 v148, s[34:35]
	s_add_i32 m0, s37, s18
	s_nop 0
	global_load_lds_dwordx4 v146, s[34:35]
	ds_read_b64_tr_b16 v[88:89], v112 offset:34816
	ds_read_b64_tr_b16 v[90:91], v112 offset:35328
	ds_read_b64_tr_b16 v[92:93], v112 offset:38912
	ds_read_b64_tr_b16 v[94:95], v112 offset:39424
	v_mfma_f32_32x32x16_bf16 v[48:63], v[76:79], v[96:99], v[48:63]
	s_waitcnt lgkmcnt(8)
	v_mfma_f32_32x32x16_bf16 v[32:47], v[76:79], v[108:111], v[32:47]
	v_mfma_f32_32x32x16_bf16 v[16:31], v[84:87], v[96:99], v[16:31]
	v_mfma_f32_32x32x16_bf16 v[0:15], v[84:87], v[108:111], v[0:15]
	ds_read_b64_tr_b16 v[76:77], v112 offset:35840
	ds_read_b64_tr_b16 v[78:79], v112 offset:36352
	ds_read_b64_tr_b16 v[84:85], v112 offset:39936
	ds_read_b64_tr_b16 v[86:87], v112 offset:40448
	ds_read_b128 v[206:209], v197 offset:4096
	ds_read_b128 v[228:231], v197 offset:6144
	ds_read_b128 v[232:235], v196 offset:4096
	ds_read_b128 v[236:239], v196 offset:6144
	ds_read_b128 v[240:243], v174
	ds_read_b128 v[244:247], v174 offset:1024
	ds_read_b128 v[248:251], v174 offset:2048
	ds_read_b128 v[186:189], v174 offset:3072
	s_waitcnt lgkmcnt(14)
	v_mfma_f32_32x32x16_bf16 v[48:63], v[72:75], v[88:91], v[48:63]
	s_waitcnt lgkmcnt(12)
	v_mfma_f32_32x32x16_bf16 v[32:47], v[72:75], v[92:95], v[32:47]
	v_mfma_f32_32x32x16_bf16 v[16:31], v[80:83], v[88:91], v[16:31]
	v_mfma_f32_32x32x16_bf16 v[0:15], v[80:83], v[92:95], v[0:15]
	s_waitcnt lgkmcnt(10)
	v_mfma_f32_32x32x16_bf16 v[48:63], v[68:71], v[76:79], v[48:63]
	s_waitcnt lgkmcnt(8)
	v_mfma_f32_32x32x16_bf16 v[32:47], v[68:71], v[84:87], v[32:47]
	v_mfma_f32_32x32x16_bf16 v[16:31], v[64:67], v[76:79], v[16:31]
	v_mfma_f32_32x32x16_bf16 v[0:15], v[64:67], v[84:87], v[0:15]
	v_mfma_f32_32x32x16_bf16 v[112:127], v[134:137], v[142:145], 0
	v_mfma_f32_32x32x16_bf16 v[96:111], v[130:133], v[142:145], 0
	v_mfma_f32_32x32x16_bf16 v[80:95], v[134:137], v[138:141], 0
	v_mfma_f32_32x32x16_bf16 v[64:79], v[130:133], v[138:141], 0
	s_waitcnt lgkmcnt(3)
	v_mfma_f32_32x32x16_bf16 v[112:127], v[158:161], v[240:243], v[112:127]
	v_mfma_f32_32x32x16_bf16 v[96:111], v[192:195], v[240:243], v[96:111]
	s_waitcnt lgkmcnt(1)
	v_mfma_f32_32x32x16_bf16 v[80:95], v[206:209], v[248:251], v[80:95]
	v_mfma_f32_32x32x16_bf16 v[64:79], v[228:231], v[248:251], v[64:79]
	v_mfma_f32_32x32x16_bf16 v[112:127], v[198:201], v[244:247], v[112:127]
	v_mfma_f32_32x32x16_bf16 v[96:111], v[202:205], v[244:247], v[96:111]
	s_waitcnt lgkmcnt(0)
	v_mfma_f32_32x32x16_bf16 v[80:95], v[232:235], v[186:189], v[80:95]
	v_mfma_f32_32x32x16_bf16 v[64:79], v[236:239], v[186:189], v[64:79]
	s_cmp_eq_u32 s30, s21
	s_cselect_b64 s[42:43], -1, 0
	s_cmp_lg_u32 s30, s21
	s_waitcnt vmcnt(2) lgkmcnt(0)
	s_barrier
	s_setprio 1
	s_nop 1
	s_cbranch_scc1 .LBB0_341
; #define ATT_DIAG_BIAS(s0, s1) do { const float dqh_ = dq - (float)(4 * hi); _Pragma("unroll") for (int r = 0; r < 16; ++r) { const float c_ = (float)((r & 3) + 8 * (r >> 2)); \
;         s0[r] = __builtin_fmaf(-sl, __builtin_fabsf(dqh_ - c_), s0[r]); s1[r] = __builtin_fmaf(-sl, __builtin_fabsf(dqh_ - (c_ + 32.f)), s1[r]); } } while (0)
;     ...
;         { const bool diag = tau == td; const float dq = (float)(tq - tau * KVBLK);
;           if (ABL & 2) { asm volatile("" : "=v"(pa0), "=v"(pa1), "=v"(pa2), "=v"(pa3), "=v"(pb0), "=v"(pb1), "=v"(pb2), "=v"(pb3) : "v"(sa0), "v"(sa1), "v"(sb0), "v"(sb1)); } else {
;           if (diag) { ATT_DIAG_BIAS(sa0, sa1); ATT_DIAG_BIAS(sb0, sb1); }
	s_lshl_b32 s34, s30, 6
	v_subrev_u32_e32 v128, s34, v171
	v_cvt_f32_i32_e32 v199, v128
	s_mov_b32 s34, 0xc2000000
	v_sub_f32_e32 v128, v199, v184
	s_mov_b32 s35, 0xc2040000
	v_pk_add_f32 v[158:159], v[128:129], s[34:35] op_sel_hi:[0,1]
	s_mov_b32 s34, -2.0
	s_mov_b32 s35, 0xc0400000
	v_pk_add_f32 v[160:161], v[128:129], s[34:35] op_sel_hi:[0,1]
	s_mov_b32 s34, 0xc2080000
	s_mov_b32 s35, 0xc20c0000
	v_pk_add_f32 v[162:163], v[128:129], s[34:35] op_sel_hi:[0,1]
	s_mov_b32 s34, 0xc1000000
	s_mov_b32 s35, 0xc1100000
	v_pk_add_f32 v[186:187], v[128:129], s[34:35] op_sel_hi:[0,1]
	s_mov_b32 s34, 0xc2200000
	s_mov_b32 s35, 0xc2240000
	v_pk_add_f32 v[188:189], v[128:129], s[34:35] op_sel_hi:[0,1]
	s_mov_b32 s34, 0xc1200000
	s_mov_b32 s35, 0xc1300000
	v_pk_add_f32 v[192:193], v[128:129], s[34:35] op_sel_hi:[0,1]
	s_mov_b32 s34, 0xc2280000
	s_mov_b32 s35, 0xc22c0000
	v_pk_add_f32 v[194:195], v[128:129], s[34:35] op_sel_hi:[0,1]
	s_mov_b32 s34, 0xc1800000
	s_mov_b32 s35, 0xc1880000
	v_pk_add_f32 v[200:201], v[128:129], s[34:35] op_sel_hi:[0,1]
	s_mov_b32 s34, 0xc2400000
	s_mov_b32 s35, 0xc2440000
	v_pk_add_f32 v[202:203], v[128:129], s[34:35] op_sel_hi:[0,1]
	s_mov_b32 s34, 0xc1900000
	s_mov_b32 s35, 0xc1980000
	v_pk_add_f32 v[204:205], v[128:129], s[34:35] op_sel_hi:[0,1]
	s_mov_b32 s34, 0xc2480000
	s_mov_b32 s35, 0xc24c0000
	v_pk_add_f32 v[206:207], v[128:129], s[34:35] op_sel_hi:[0,1]
	s_mov_b32 s34, 0xc1c00000
	s_mov_b32 s35, 0xc1c80000
	v_pk_add_f32 v[208:209], v[128:129], s[34:35] op_sel_hi:[0,1]
	s_mov_b32 s34, 0xc2600000
	s_mov_b32 s35, 0xc2640000
	v_pk_add_f32 v[210:211], v[128:129], s[34:35] op_sel_hi:[0,1]
	s_mov_b32 s34, 0xc1d00000
	s_mov_b32 s35, 0xc1d80000
	v_pk_add_f32 v[214:215], v[128:129], s[34:35] op_sel_hi:[0,1]
	s_mov_b32 s34, 0xc2680000
	s_mov_b32 s35, 0xc26c0000
	v_add_f32_e32 v155, -1.0, v128
	v_pk_add_f32 v[222:223], v[128:129], s[34:35] op_sel_hi:[0,1]
	v_and_b32_e32 v159, 0x7fffffff, v159
	v_and_b32_e32 v158, 0x7fffffff, v158
	v_and_b32_e32 v163, 0x7fffffff, v163
	v_and_b32_e32 v162, 0x7fffffff, v162
	v_and_b32_e32 v187, 0x7fffffff, v187
	v_and_b32_e32 v186, 0x7fffffff, v186
	v_and_b32_e32 v189, 0x7fffffff, v189
	v_and_b32_e32 v188, 0x7fffffff, v188
	v_and_b32_e32 v193, 0x7fffffff, v193
	v_and_b32_e32 v192, 0x7fffffff, v192
	v_and_b32_e32 v195, 0x7fffffff, v195
	v_and_b32_e32 v194, 0x7fffffff, v194
	v_and_b32_e32 v201, 0x7fffffff, v201
	v_and_b32_e32 v200, 0x7fffffff, v200
	v_and_b32_e32 v203, 0x7fffffff, v203
	v_and_b32_e32 v202, 0x7fffffff, v202
	v_and_b32_e32 v205, 0x7fffffff, v205
	v_and_b32_e32 v204, 0x7fffffff, v204
	v_and_b32_e32 v207, 0x7fffffff, v207
	v_and_b32_e32 v206, 0x7fffffff, v206
	v_and_b32_e32 v209, 0x7fffffff, v209
	v_and_b32_e32 v208, 0x7fffffff, v208
	v_and_b32_e32 v211, 0x7fffffff, v211
	v_and_b32_e32 v210, 0x7fffffff, v210
	v_and_b32_e32 v215, 0x7fffffff, v215
	v_and_b32_e32 v214, 0x7fffffff, v214
	v_and_b32_e32 v223, 0x7fffffff, v223
	v_and_b32_e32 v222, 0x7fffffff, v222
	v_and_b32_e32 v161, 0x7fffffff, v161
	v_and_b32_e32 v160, 0x7fffffff, v160
	v_and_b32_e32 v228, 0x7fffffff, v128
	v_and_b32_e32 v229, 0x7fffffff, v155
	v_mov_b32_e32 v155, v154
	v_pk_fma_f32 v[94:95], v[154:155], v[214:215], v[94:95]
	v_pk_fma_f32 v[92:93], v[154:155], v[208:209], v[92:93]
	v_pk_fma_f32 v[90:91], v[154:155], v[204:205], v[90:91]
	v_pk_fma_f32 v[88:89], v[154:155], v[200:201], v[88:89]
	v_pk_fma_f32 v[86:87], v[154:155], v[192:193], v[86:87]
	v_pk_fma_f32 v[84:85], v[154:155], v[186:187], v[84:85]
	v_pk_fma_f32 v[82:83], v[154:155], v[160:161], v[82:83]
	v_pk_fma_f32 v[80:81], v[156:157], v[228:229], v[80:81]
	v_pk_fma_f32 v[78:79], v[154:155], v[222:223], v[78:79]
	v_pk_fma_f32 v[76:77], v[154:155], v[210:211], v[76:77]
	v_pk_fma_f32 v[74:75], v[154:155], v[206:207], v[74:75]
	v_pk_fma_f32 v[72:73], v[154:155], v[202:203], v[72:73]
	v_pk_fma_f32 v[70:71], v[154:155], v[194:195], v[70:71]
	v_pk_fma_f32 v[68:69], v[154:155], v[188:189], v[68:69]
	v_pk_fma_f32 v[66:67], v[154:155], v[162:163], v[66:67]
	v_pk_fma_f32 v[64:65], v[156:157], v[158:159], v[64:65]
	v_pk_fma_f32 v[126:127], v[154:155], v[214:215], v[126:127]
	v_pk_fma_f32 v[124:125], v[154:155], v[208:209], v[124:125]
	v_pk_fma_f32 v[122:123], v[154:155], v[204:205], v[122:123]
	v_pk_fma_f32 v[120:121], v[154:155], v[200:201], v[120:121]
	v_pk_fma_f32 v[118:119], v[154:155], v[192:193], v[118:119]
	v_pk_fma_f32 v[116:117], v[154:155], v[186:187], v[116:117]
	v_pk_fma_f32 v[114:115], v[154:155], v[160:161], v[114:115]
	v_pk_fma_f32 v[112:113], v[156:157], v[228:229], v[112:113]
	v_pk_fma_f32 v[110:111], v[154:155], v[222:223], v[110:111]
	v_pk_fma_f32 v[108:109], v[154:155], v[210:211], v[108:109]
	v_pk_fma_f32 v[106:107], v[154:155], v[206:207], v[106:107]
	v_pk_fma_f32 v[104:105], v[154:155], v[202:203], v[104:105]
	v_pk_fma_f32 v[102:103], v[154:155], v[194:195], v[102:103]
	v_pk_fma_f32 v[100:101], v[154:155], v[188:189], v[100:101]
	v_pk_fma_f32 v[98:99], v[154:155], v[162:163], v[98:99]
	v_pk_fma_f32 v[96:97], v[156:157], v[158:159], v[96:97]
